# attention phase hand-written: 3-deep K/V register ring with counted waits, XCD-local unit order, weights as p - p*f, exit once all carried products <= 2^-134
# speedup vs baseline: 1.0922x; 1.0025x over previous
; __device__ __forceinline__ void attn_phase(const Ptrs& P, int gw, int NGW, int lane) {
;     const bf16x8* QF = (const bf16x8*)(P.ws + WS_U1); const bf16x8* KF = QF + (size_t)M * AW / 8; const v2u* GF = (const v2u*)(KF + (size_t)M * AW / 8);
;     const bf16x8* VF = (const bf16x8*)(P.ws + WS_VT); bf16* OG = (bf16*)(P.ws + WS_OG);
;     const int r = lane & 31, hh = lane >> 5;
;     for (int u = gw; u < BATCH * AH * (SEQ / 32); u += NGW) {
;         const int qt = u & 127, bhh = u >> 7, b = bhh >> 4, h = bhh & 15;
;         const size_t rowbase = (size_t)b * SEQ;
;         bf16x8 qf[4], kf[4];
;         { const bf16x8* qp = QF + (size_t)(bhh * 128 + qt) * 256 + lane;
; #pragma unroll
;           for (int ks = 0; ks < 4; ++ks) qf[ks] = qp[ks * 64]; }
;         const bf16x8* kbase = KF + (size_t)bhh * 128 * 256 + lane;
;         const bf16x8* vbase = VF + (size_t)bhh * 128 * 256 + lane;
;         bf16x8 k1[4], k2[4], vf[2][2], v1[2][2];
;         { const int q1 = qt > 0 ? qt - 1 : 0, q2 = qt > 1 ? qt - 2 : 0;
; #pragma unroll
;           for (int ks = 0; ks < 4; ++ks) { kf[ks] = kbase[(size_t)qt * 256 + ks * 64]; k1[ks] = kbase[(size_t)q1 * 256 + ks * 64]; k2[ks] = kbase[(size_t)q2 * 256 + ks * 64]; }
; #pragma unroll
;           for (int dt = 0; dt < 2; ++dt)
; #pragma unroll
;               for (int s = 0; s < 2; ++s) { vf[dt][s] = vbase[(size_t)qt * 256 + (dt * 2 + s) * 64]; v1[dt][s] = vbase[(size_t)q1 * 256 + (dt * 2 + s) * 64]; } }
;         v2u gq_[8];
;         { const v2u* gp_ = GF + (size_t)(bhh * 128 + qt) * 512 + lane;
; #pragma unroll
;           for (int j = 0; j < 8; ++j) gq_[j] = gp_[j * 64]; }
;         f32x16 o0, o1;
; #pragma unroll
;         for (int i = 0; i < 16; ++i) { o0[i] = 0.f; o1[i] = 0.f; }
;         float Pc = 1.0f;
.LBB0_635:
	s_cmp_lt_i32 s56, 7
	s_cselect_b64 s[4:5], -1, 0
	s_and_b64 s[38:39], s[4:5], s[2:3]
	s_andn2_b64 vcc, exec, s[38:39]
	s_cbranch_vccnz .LBB0_642
	s_cmpk_gt_i32 s60, 0x1fff
	s_cbranch_scc1 .LBB0_642
	s_waitcnt lgkmcnt(0)
	v_lshlrev_b32_e32 v185, 4, v232
	v_lshlrev_b32_e32 v233, 3, v232
	v_and_b32_e32 v234, 31, v232
	v_lshrrev_b32_e32 v235, 5, v232
	v_lshlrev_b32_e32 v236, 2, v235
	v_lshlrev_b32_e32 v238, 4, v235
	v_cmp_lt_u32_e64 s[4:5], v236, v234
	v_or_b32_e32 v237, 1, v236
	v_cmp_lt_u32_e64 s[6:7], v237, v234
	v_or_b32_e32 v237, 2, v236
	v_cmp_lt_u32_e64 s[8:9], v237, v234
	v_or_b32_e32 v237, 3, v236
	v_cmp_lt_u32_e64 s[10:11], v237, v234
	v_or_b32_e32 v237, 8, v236
	v_cmp_lt_u32_e64 s[12:13], v237, v234
	v_or_b32_e32 v237, 9, v236
	v_cmp_lt_u32_e64 s[14:15], v237, v234
	v_or_b32_e32 v237, 10, v236
	v_cmp_lt_u32_e64 s[16:17], v237, v234
	v_or_b32_e32 v237, 11, v236
	v_cmp_lt_u32_e64 s[18:19], v237, v234
	v_or_b32_e32 v237, 16, v236
	v_cmp_lt_u32_e64 s[20:21], v237, v234
	v_or_b32_e32 v237, 17, v236
	v_cmp_lt_u32_e64 s[22:23], v237, v234
	v_or_b32_e32 v237, 18, v236
	v_cmp_lt_u32_e64 s[24:25], v237, v234
	v_or_b32_e32 v237, 19, v236
	v_cmp_lt_u32_e64 s[26:27], v237, v234
	v_or_b32_e32 v237, 24, v236
	v_cmp_lt_u32_e64 s[28:29], v237, v234
	v_or_b32_e32 v237, 25, v236
	v_cmp_lt_u32_e64 s[30:31], v237, v234
	v_or_b32_e32 v237, 26, v236
	v_cmp_lt_u32_e64 s[34:35], v237, v234
	v_or_b32_e32 v237, 27, v236
	v_cmp_lt_u32_e64 s[36:37], v237, v234
	v_cmp_gt_u32_e64 s[2:3], 32, v232
	s_add_u32 s44, s54, 0x3800000
	s_addc_u32 s45, s55, 0
	s_add_u32 s46, s54, 0x5800000
	s_addc_u32 s47, s55, 0
	s_add_u32 s48, s54, 0x9c00000
	s_addc_u32 s49, s55, 0
	s_add_u32 s50, s54, 0x7800000
	s_addc_u32 s51, s55, 0
	s_add_u32 s42, s54, 0xbc00000
	s_addc_u32 s43, s55, 0
	s_mov_b32 s58, s60
	s_cmpk_lg_i32 s64, 0x100
	s_cbranch_scc1 .Lp6_nomap
	s_and_b32 s78, s33, 7
	s_lshl_b32 s78, s78, 8
	s_lshr_b32 s79, s33, 7
	s_lshl_b32 s79, s79, 7
	s_or_b32 s78, s78, s79
	s_bfe_u32 s79, s33, 0x40003
	s_lshl_b32 s79, s79, 3
	s_or_b32 s78, s78, s79
	s_and_b32 s79, s60, 7
	s_or_b32 s58, s78, s79
.Lp6_nomap:
	s_and_b32 s63, s58, 0x7f
	s_lshr_b32 s69, s58, 7
	s_lshl_b32 s78, s58, 12
	s_add_u32 s74, s44, s78
	s_addc_u32 s75, s45, 0
	s_add_u32 s76, s50, s78
	s_addc_u32 s77, s51, 0
	global_load_dwordx4 v[48:51], v185, s[74:75]
	global_load_dwordx4 v[52:55], v185, s[74:75] offset:1024
	global_load_dwordx4 v[56:59], v185, s[74:75] offset:2048
	global_load_dwordx4 v[60:63], v185, s[74:75] offset:3072
	global_load_dwordx2 v[160:161], v233, s[76:77]
	global_load_dwordx2 v[162:163], v233, s[76:77] offset:512
	global_load_dwordx2 v[164:165], v233, s[76:77] offset:1024
	global_load_dwordx2 v[166:167], v233, s[76:77] offset:1536
	global_load_dwordx2 v[168:169], v233, s[76:77] offset:2048
	global_load_dwordx2 v[170:171], v233, s[76:77] offset:2560
	global_load_dwordx2 v[172:173], v233, s[76:77] offset:3072
	global_load_dwordx2 v[174:175], v233, s[76:77] offset:3584
	s_lshl_b32 s78, s69, 19
	s_add_u32 s70, s46, s78
	s_addc_u32 s71, s47, 0
	s_add_u32 s72, s48, s78
	s_addc_u32 s73, s49, 0
	s_lshl_b32 s78, s63, 12
	s_add_u32 s74, s70, s78
	s_addc_u32 s75, s71, 0
	s_add_u32 s76, s72, s78
	s_addc_u32 s77, s73, 0
	global_load_dwordx4 v[64:67], v185, s[74:75]
	global_load_dwordx4 v[68:71], v185, s[74:75] offset:1024
	global_load_dwordx4 v[72:75], v185, s[74:75] offset:2048
	global_load_dwordx4 v[76:79], v185, s[74:75] offset:3072
	global_load_dwordx4 v[80:83], v185, s[76:77]
	global_load_dwordx4 v[84:87], v185, s[76:77] offset:1024
	global_load_dwordx4 v[88:91], v185, s[76:77] offset:2048
	global_load_dwordx4 v[92:95], v185, s[76:77] offset:3072
	s_sub_i32 s78, s63, 1
	s_max_i32 s78, s78, 0
	s_lshl_b32 s78, s78, 12
	s_add_u32 s74, s70, s78
	s_addc_u32 s75, s71, 0
	s_add_u32 s76, s72, s78
	s_addc_u32 s77, s73, 0
	global_load_dwordx4 v[96:99], v185, s[74:75]
	global_load_dwordx4 v[100:103], v185, s[74:75] offset:1024
	global_load_dwordx4 v[104:107], v185, s[74:75] offset:2048
	global_load_dwordx4 v[108:111], v185, s[74:75] offset:3072
	global_load_dwordx4 v[112:115], v185, s[76:77]
	global_load_dwordx4 v[116:119], v185, s[76:77] offset:1024
	global_load_dwordx4 v[120:123], v185, s[76:77] offset:2048
	global_load_dwordx4 v[124:127], v185, s[76:77] offset:3072
	s_sub_i32 s78, s63, 2
	s_max_i32 s78, s78, 0
	s_lshl_b32 s78, s78, 12
	s_add_u32 s74, s70, s78
	s_addc_u32 s75, s71, 0
	s_add_u32 s76, s72, s78
	s_addc_u32 s77, s73, 0
	global_load_dwordx4 v[128:131], v185, s[74:75]
	global_load_dwordx4 v[132:135], v185, s[74:75] offset:1024
	global_load_dwordx4 v[136:139], v185, s[74:75] offset:2048
	global_load_dwordx4 v[140:143], v185, s[74:75] offset:3072
	global_load_dwordx4 v[144:147], v185, s[76:77]
	global_load_dwordx4 v[148:151], v185, s[76:77] offset:1024
	global_load_dwordx4 v[152:155], v185, s[76:77] offset:2048
	global_load_dwordx4 v[156:159], v185, s[76:77] offset:3072
; __device__ __forceinline__ void attn_phase(const Ptrs& P, int gw, int NGW, int lane) {
;     ...
;             bf16x8 k3[4], v2[2][2];
;             { const int t3 = kt > 2 ? kt - 3 : 0, t2 = kt > 1 ? kt - 2 : 0;
; #pragma unroll
;               for (int ks = 0; ks < 4; ++ks) k3[ks] = kbase[(size_t)t3 * 256 + ks * 64];
; #pragma unroll
;               for (int dt = 0; dt < 2; ++dt)
; #pragma unroll
;                   for (int s = 0; s < 2; ++s) v2[dt][s] = vbase[(size_t)t2 * 256 + (dt * 2 + s) * 64]; }
;             f32x16 sa;
; #pragma unroll
;             for (int i = 0; i < 16; ++i) sa[i] = 0.f;
; #pragma unroll
;             for (int ks = 0; ks < 4; ++ks) sa = MFMA32(kf[ks], qf[ks], sa);
;             float beta[16], f[16];
;             const bool diag = (kt == qt);
; #pragma unroll
;             for (int i = 0; i < 16; ++i) { float ff = rcpf_(1.0f + ex2(sa[i])), bt = 1.0f - ff;
;                 if (diag) { const bool valid = crow(i, hh) < r; bt = valid ? bt : 0.0f; ff = valid ? ff : 1.0f; }
;                 beta[i] = bt; f[i] = ff; }
;             float gp[4], ot[4], pr[4];
; #pragma unroll
;             for (int g = 0; g < 4; ++g) { gp[g] = (f[4 * g] * f[4 * g + 1]) * (f[4 * g + 2] * f[4 * g + 3]);
;                 const auto rr = __builtin_amdgcn_permlane32_swap(__float_as_uint(gp[g]), __float_as_uint(gp[g]), false, false);
;                 ot[g] = __uint_as_float(rr[1]); pr[g] = __uint_as_float(rr[0]) * __uint_as_float(rr[1]); }
;             float suf = Pc; float att[16];
; #pragma unroll
;             for (int g = 3; g >= 0; --g) { float p = (hh == 0) ? suf * ot[g] : suf;
;                 att[4 * g + 3] = beta[4 * g + 3] * p; p *= f[4 * g + 3];
;                 att[4 * g + 2] = beta[4 * g + 2] * p; p *= f[4 * g + 2];
;                 att[4 * g + 1] = beta[4 * g + 1] * p; p *= f[4 * g + 1];
;                 att[4 * g] = beta[4 * g] * p;
;                 suf *= pr[g]; }
;             Pc = suf;
; #pragma unroll
;             for (int i = 0; i < 16; ++i) asm("" : "+v"(att[i]));
;             bf16x8 pf[2];
; #pragma unroll
;             for (int s = 0; s < 2; ++s) { v4u t; t.x = pk2(att[8 * s], att[8 * s + 1]); t.y = pk2(att[8 * s + 2], att[8 * s + 3]); t.z = pk2(att[8 * s + 4], att[8 * s + 5]); t.w = pk2(att[8 * s + 6], att[8 * s + 7]); pf[s] = __builtin_bit_cast(bf16x8, t); }
; #pragma unroll
.Lp6_unit:
	s_mov_b32 s68, s63
	v_mov_b32_e32 v229, 1.0
	s_waitcnt vmcnt(20)
	v_mfma_f32_32x32x16_bf16 v[32:47], v[64:67], v[48:51], 0
	v_mfma_f32_32x32x16_bf16 v[32:47], v[68:71], v[52:55], v[32:47]
	v_mfma_f32_32x32x16_bf16 v[32:47], v[72:75], v[56:59], v[32:47]
	v_mfma_f32_32x32x16_bf16 v[32:47], v[76:79], v[60:63], v[32:47]
	s_sub_i32 s80, s68, 3
	s_max_i32 s80, s80, 0
	s_lshl_b32 s80, s80, 12
	s_add_u32 s74, s70, s80
	s_addc_u32 s75, s71, 0
	s_add_u32 s76, s72, s80
	s_addc_u32 s77, s73, 0
	s_nop 4
	v_exp_f32_e32 v32, v32
	v_exp_f32_e32 v33, v33
	v_exp_f32_e32 v34, v34
	v_exp_f32_e32 v35, v35
	v_exp_f32_e32 v36, v36
	v_exp_f32_e32 v37, v37
	v_exp_f32_e32 v38, v38
	v_exp_f32_e32 v39, v39
	v_exp_f32_e32 v40, v40
	v_exp_f32_e32 v41, v41
	v_exp_f32_e32 v42, v42
	v_exp_f32_e32 v43, v43
	v_exp_f32_e32 v44, v44
	v_exp_f32_e32 v45, v45
	v_exp_f32_e32 v46, v46
	v_exp_f32_e32 v47, v47
	v_add_f32_e32 v32, 1.0, v32
	v_add_f32_e32 v33, 1.0, v33
	v_add_f32_e32 v34, 1.0, v34
	v_add_f32_e32 v35, 1.0, v35
	v_add_f32_e32 v36, 1.0, v36
	v_add_f32_e32 v37, 1.0, v37
	v_add_f32_e32 v38, 1.0, v38
	v_add_f32_e32 v39, 1.0, v39
	v_add_f32_e32 v40, 1.0, v40
	v_add_f32_e32 v41, 1.0, v41
	v_add_f32_e32 v42, 1.0, v42
	v_add_f32_e32 v43, 1.0, v43
	v_add_f32_e32 v44, 1.0, v44
	v_add_f32_e32 v45, 1.0, v45
	v_add_f32_e32 v46, 1.0, v46
	v_add_f32_e32 v47, 1.0, v47
	v_rcp_f32_e32 v32, v32
	v_rcp_f32_e32 v33, v33
	v_rcp_f32_e32 v34, v34
	v_rcp_f32_e32 v35, v35
	v_rcp_f32_e32 v36, v36
	v_rcp_f32_e32 v37, v37
	v_rcp_f32_e32 v38, v38
	v_rcp_f32_e32 v39, v39
	v_rcp_f32_e32 v40, v40
	v_rcp_f32_e32 v41, v41
	v_rcp_f32_e32 v42, v42
	v_rcp_f32_e32 v43, v43
	v_rcp_f32_e32 v44, v44
	v_rcp_f32_e32 v45, v45
	v_rcp_f32_e32 v46, v46
	v_rcp_f32_e32 v47, v47
	v_cndmask_b32_e64 v32, 1.0, v32, s[4:5]
	v_cndmask_b32_e64 v33, 1.0, v33, s[6:7]
	v_cndmask_b32_e64 v34, 1.0, v34, s[8:9]
	v_cndmask_b32_e64 v35, 1.0, v35, s[10:11]
	v_cndmask_b32_e64 v36, 1.0, v36, s[12:13]
	v_cndmask_b32_e64 v37, 1.0, v37, s[14:15]
	v_cndmask_b32_e64 v38, 1.0, v38, s[16:17]
	v_cndmask_b32_e64 v39, 1.0, v39, s[18:19]
	v_cndmask_b32_e64 v40, 1.0, v40, s[20:21]
	v_cndmask_b32_e64 v41, 1.0, v41, s[22:23]
	v_cndmask_b32_e64 v42, 1.0, v42, s[24:25]
	v_cndmask_b32_e64 v43, 1.0, v43, s[26:27]
	v_cndmask_b32_e64 v44, 1.0, v44, s[28:29]
	v_cndmask_b32_e64 v45, 1.0, v45, s[30:31]
	v_cndmask_b32_e64 v46, 1.0, v46, s[34:35]
	v_cndmask_b32_e64 v47, 1.0, v47, s[36:37]
	v_mul_f32_e32 v230, v32, v33
	v_mul_f32_e32 v231, v34, v35
	v_mul_f32_e32 v219, v230, v231
	v_mul_f32_e32 v230, v36, v37
	v_mul_f32_e32 v231, v38, v39
	v_mul_f32_e32 v220, v230, v231
	v_mul_f32_e32 v230, v40, v41
	v_mul_f32_e32 v231, v42, v43
	v_mul_f32_e32 v221, v230, v231
	v_mul_f32_e32 v230, v44, v45
	v_mul_f32_e32 v231, v46, v47
	v_mul_f32_e32 v222, v230, v231
	v_mov_b32_e32 v223, v219
	v_mov_b32_e32 v224, v220
	v_mov_b32_e32 v225, v221
	v_mov_b32_e32 v226, v222
	s_nop 1
	v_permlane32_swap_b32_e32 v219, v223
	v_permlane32_swap_b32_e32 v220, v224
	v_permlane32_swap_b32_e32 v221, v225
	v_permlane32_swap_b32_e32 v222, v226
	v_mul_f32_e32 v228, v229, v226
	v_cndmask_b32_e64 v228, v229, v228, s[2:3]
	v_mul_f32_e32 v230, v228, v47
	v_sub_f32_e32 v218, v228, v230
	v_mul_f32_e32 v228, v230, v46
	v_sub_f32_e32 v217, v230, v228
	v_mul_f32_e32 v230, v228, v45
	v_sub_f32_e32 v216, v228, v230
	v_mul_f32_e32 v228, v230, v44
	v_sub_f32_e32 v215, v230, v228
	v_mul_f32_e32 v227, v222, v226
	v_mul_f32_e32 v229, v229, v227
	v_mul_f32_e32 v228, v229, v225
	v_cndmask_b32_e64 v228, v229, v228, s[2:3]
	v_mul_f32_e32 v230, v228, v43
	v_sub_f32_e32 v214, v228, v230
	v_mul_f32_e32 v228, v230, v42
	v_sub_f32_e32 v213, v230, v228
	v_mul_f32_e32 v230, v228, v41
	v_sub_f32_e32 v212, v228, v230
	v_mul_f32_e32 v228, v230, v40
	v_sub_f32_e32 v211, v230, v228
	v_mul_f32_e32 v227, v221, v225
	v_mul_f32_e32 v229, v229, v227
	v_mul_f32_e32 v228, v229, v224
	v_cndmask_b32_e64 v228, v229, v228, s[2:3]
	v_mul_f32_e32 v230, v228, v39
	v_sub_f32_e32 v210, v228, v230
	v_mul_f32_e32 v228, v230, v38
	v_sub_f32_e32 v209, v230, v228
	v_mul_f32_e32 v230, v228, v37
	v_sub_f32_e32 v208, v228, v230
	v_mul_f32_e32 v228, v230, v36
	v_sub_f32_e32 v207, v230, v228
	v_mul_f32_e32 v227, v220, v224
	v_mul_f32_e32 v229, v229, v227
	v_mul_f32_e32 v228, v229, v223
	v_cndmask_b32_e64 v228, v229, v228, s[2:3]
	v_mul_f32_e32 v230, v228, v35
	v_sub_f32_e32 v206, v228, v230
	v_mul_f32_e32 v228, v230, v34
	v_sub_f32_e32 v205, v230, v228
	v_mul_f32_e32 v230, v228, v33
	v_sub_f32_e32 v204, v228, v230
	v_mul_f32_e32 v228, v230, v32
	v_sub_f32_e32 v203, v230, v228
	v_mul_f32_e32 v227, v219, v223
	v_mul_f32_e32 v229, v229, v227
	v_cvt_pk_bf16_f32 v176, v203, v204
	v_cvt_pk_bf16_f32 v177, v205, v206
	v_cvt_pk_bf16_f32 v178, v207, v208
	v_cvt_pk_bf16_f32 v179, v209, v210
	v_cvt_pk_bf16_f32 v180, v211, v212
	v_cvt_pk_bf16_f32 v181, v213, v214
	v_cvt_pk_bf16_f32 v182, v215, v216
	v_cvt_pk_bf16_f32 v183, v217, v218
	v_cmp_nge_f32_e32 vcc, 0x8000, v229
	s_waitcnt vmcnt(16)
	s_nop 0
	v_mfma_f32_32x32x16_bf16 v[0:15], v[80:83], v[176:179], 0
	v_mfma_f32_32x32x16_bf16 v[16:31], v[88:91], v[176:179], 0
	v_mfma_f32_32x32x16_bf16 v[0:15], v[84:87], v[180:183], v[0:15]
	v_mfma_f32_32x32x16_bf16 v[16:31], v[92:95], v[180:183], v[16:31]
	s_cmp_eq_u64 vcc, 0
	s_cbranch_scc1 .Lp6_epi
	s_cmp_eq_u32 s68, 0
	s_cbranch_scc1 .Lp6_epi
	s_add_i32 s68, s68, -1
	global_load_dwordx4 v[64:67], v185, s[74:75]
	global_load_dwordx4 v[68:71], v185, s[74:75] offset:1024
	global_load_dwordx4 v[72:75], v185, s[74:75] offset:2048
	global_load_dwordx4 v[76:79], v185, s[74:75] offset:3072
	global_load_dwordx4 v[80:83], v185, s[76:77]
	global_load_dwordx4 v[84:87], v185, s[76:77] offset:1024
	global_load_dwordx4 v[88:91], v185, s[76:77] offset:2048
	global_load_dwordx4 v[92:95], v185, s[76:77] offset:3072
; __device__ __forceinline__ void attn_phase(const Ptrs& P, int gw, int NGW, int lane) {
;     ...
;             bf16x8 k3[4], v2[2][2];
;             { const int t3 = kt > 2 ? kt - 3 : 0, t2 = kt > 1 ? kt - 2 : 0;
; #pragma unroll
;               for (int ks = 0; ks < 4; ++ks) k3[ks] = kbase[(size_t)t3 * 256 + ks * 64];
; #pragma unroll
;               for (int dt = 0; dt < 2; ++dt)
; #pragma unroll
;                   for (int s = 0; s < 2; ++s) v2[dt][s] = vbase[(size_t)t2 * 256 + (dt * 2 + s) * 64]; }
;             f32x16 sa;
; #pragma unroll
;             for (int i = 0; i < 16; ++i) sa[i] = 0.f;
; #pragma unroll
;             for (int ks = 0; ks < 4; ++ks) sa = MFMA32(kf[ks], qf[ks], sa);
;             float beta[16], f[16];
;             const bool diag = (kt == qt);
; #pragma unroll
;             for (int i = 0; i < 16; ++i) { float ff = rcpf_(1.0f + ex2(sa[i])), bt = 1.0f - ff;
;                 if (diag) { const bool valid = crow(i, hh) < r; bt = valid ? bt : 0.0f; ff = valid ? ff : 1.0f; }
;                 beta[i] = bt; f[i] = ff; }
;             float gp[4], ot[4], pr[4];
; #pragma unroll
;             for (int g = 0; g < 4; ++g) { gp[g] = (f[4 * g] * f[4 * g + 1]) * (f[4 * g + 2] * f[4 * g + 3]);
;                 const auto rr = __builtin_amdgcn_permlane32_swap(__float_as_uint(gp[g]), __float_as_uint(gp[g]), false, false);
;                 ot[g] = __uint_as_float(rr[1]); pr[g] = __uint_as_float(rr[0]) * __uint_as_float(rr[1]); }
;             float suf = Pc; float att[16];
; #pragma unroll
;             for (int g = 3; g >= 0; --g) { float p = (hh == 0) ? suf * ot[g] : suf;
;                 att[4 * g + 3] = beta[4 * g + 3] * p; p *= f[4 * g + 3];
;                 att[4 * g + 2] = beta[4 * g + 2] * p; p *= f[4 * g + 2];
;                 att[4 * g + 1] = beta[4 * g + 1] * p; p *= f[4 * g + 1];
;                 att[4 * g] = beta[4 * g] * p;
;                 suf *= pr[g]; }
;             Pc = suf;
; #pragma unroll
;             for (int i = 0; i < 16; ++i) asm("" : "+v"(att[i]));
;             bf16x8 pf[2];
; #pragma unroll
;             for (int s = 0; s < 2; ++s) { v4u t; t.x = pk2(att[8 * s], att[8 * s + 1]); t.y = pk2(att[8 * s + 2], att[8 * s + 3]); t.z = pk2(att[8 * s + 4], att[8 * s + 5]); t.w = pk2(att[8 * s + 6], att[8 * s + 7]); pf[s] = __builtin_bit_cast(bf16x8, t); }
; #pragma unroll
.Lp6_loop:
	s_waitcnt vmcnt(20)
	v_mfma_f32_32x32x16_bf16 v[32:47], v[96:99], v[48:51], 0
	v_mfma_f32_32x32x16_bf16 v[32:47], v[100:103], v[52:55], v[32:47]
	v_mfma_f32_32x32x16_bf16 v[32:47], v[104:107], v[56:59], v[32:47]
	v_mfma_f32_32x32x16_bf16 v[32:47], v[108:111], v[60:63], v[32:47]
	s_sub_i32 s80, s68, 3
	s_max_i32 s80, s80, 0
	s_lshl_b32 s80, s80, 12
	s_add_u32 s74, s70, s80
	s_addc_u32 s75, s71, 0
	s_add_u32 s76, s72, s80
	s_addc_u32 s77, s73, 0
	s_nop 4
	v_exp_f32_e32 v32, v32
	v_exp_f32_e32 v33, v33
	v_exp_f32_e32 v34, v34
	v_exp_f32_e32 v35, v35
	v_exp_f32_e32 v36, v36
	v_exp_f32_e32 v37, v37
	v_exp_f32_e32 v38, v38
	v_exp_f32_e32 v39, v39
	v_exp_f32_e32 v40, v40
	v_exp_f32_e32 v41, v41
	v_exp_f32_e32 v42, v42
	v_exp_f32_e32 v43, v43
	v_exp_f32_e32 v44, v44
	v_exp_f32_e32 v45, v45
	v_exp_f32_e32 v46, v46
	v_exp_f32_e32 v47, v47
	v_add_f32_e32 v32, 1.0, v32
	v_add_f32_e32 v33, 1.0, v33
	v_add_f32_e32 v34, 1.0, v34
	v_add_f32_e32 v35, 1.0, v35
	v_add_f32_e32 v36, 1.0, v36
	v_add_f32_e32 v37, 1.0, v37
	v_add_f32_e32 v38, 1.0, v38
	v_add_f32_e32 v39, 1.0, v39
	v_add_f32_e32 v40, 1.0, v40
	v_add_f32_e32 v41, 1.0, v41
	v_add_f32_e32 v42, 1.0, v42
	v_add_f32_e32 v43, 1.0, v43
	v_add_f32_e32 v44, 1.0, v44
	v_add_f32_e32 v45, 1.0, v45
	v_add_f32_e32 v46, 1.0, v46
	v_add_f32_e32 v47, 1.0, v47
	v_rcp_f32_e32 v32, v32
	v_rcp_f32_e32 v33, v33
	v_rcp_f32_e32 v34, v34
	v_rcp_f32_e32 v35, v35
	v_rcp_f32_e32 v36, v36
	v_rcp_f32_e32 v37, v37
	v_rcp_f32_e32 v38, v38
	v_rcp_f32_e32 v39, v39
	v_rcp_f32_e32 v40, v40
	v_rcp_f32_e32 v41, v41
	v_rcp_f32_e32 v42, v42
	v_rcp_f32_e32 v43, v43
	v_rcp_f32_e32 v44, v44
	v_rcp_f32_e32 v45, v45
	v_rcp_f32_e32 v46, v46
	v_rcp_f32_e32 v47, v47
	v_mul_f32_e32 v230, v32, v33
	v_mul_f32_e32 v231, v34, v35
	v_mul_f32_e32 v219, v230, v231
	v_mul_f32_e32 v230, v36, v37
	v_mul_f32_e32 v231, v38, v39
	v_mul_f32_e32 v220, v230, v231
	v_mul_f32_e32 v230, v40, v41
	v_mul_f32_e32 v231, v42, v43
	v_mul_f32_e32 v221, v230, v231
	v_mul_f32_e32 v230, v44, v45
	v_mul_f32_e32 v231, v46, v47
	v_mul_f32_e32 v222, v230, v231
	v_mov_b32_e32 v223, v219
	v_mov_b32_e32 v224, v220
	v_mov_b32_e32 v225, v221
	v_mov_b32_e32 v226, v222
	s_nop 1
	v_permlane32_swap_b32_e32 v219, v223
	v_permlane32_swap_b32_e32 v220, v224
	v_permlane32_swap_b32_e32 v221, v225
	v_permlane32_swap_b32_e32 v222, v226
	v_mul_f32_e32 v228, v229, v226
	v_cndmask_b32_e64 v228, v229, v228, s[2:3]
	v_mul_f32_e32 v230, v228, v47
	v_sub_f32_e32 v218, v228, v230
	v_mul_f32_e32 v228, v230, v46
	v_sub_f32_e32 v217, v230, v228
	v_mul_f32_e32 v230, v228, v45
	v_sub_f32_e32 v216, v228, v230
	v_mul_f32_e32 v228, v230, v44
	v_sub_f32_e32 v215, v230, v228
	v_mul_f32_e32 v227, v222, v226
	v_mul_f32_e32 v229, v229, v227
	v_mul_f32_e32 v228, v229, v225
	v_cndmask_b32_e64 v228, v229, v228, s[2:3]
	v_mul_f32_e32 v230, v228, v43
	v_sub_f32_e32 v214, v228, v230
	v_mul_f32_e32 v228, v230, v42
	v_sub_f32_e32 v213, v230, v228
	v_mul_f32_e32 v230, v228, v41
	v_sub_f32_e32 v212, v228, v230
	v_mul_f32_e32 v228, v230, v40
	v_sub_f32_e32 v211, v230, v228
	v_mul_f32_e32 v227, v221, v225
	v_mul_f32_e32 v229, v229, v227
	v_mul_f32_e32 v228, v229, v224
	v_cndmask_b32_e64 v228, v229, v228, s[2:3]
	v_mul_f32_e32 v230, v228, v39
	v_sub_f32_e32 v210, v228, v230
	v_mul_f32_e32 v228, v230, v38
	v_sub_f32_e32 v209, v230, v228
	v_mul_f32_e32 v230, v228, v37
	v_sub_f32_e32 v208, v228, v230
	v_mul_f32_e32 v228, v230, v36
	v_sub_f32_e32 v207, v230, v228
	v_mul_f32_e32 v227, v220, v224
	v_mul_f32_e32 v229, v229, v227
	v_mul_f32_e32 v228, v229, v223
	v_cndmask_b32_e64 v228, v229, v228, s[2:3]
	v_mul_f32_e32 v230, v228, v35
	v_sub_f32_e32 v206, v228, v230
	v_mul_f32_e32 v228, v230, v34
	v_sub_f32_e32 v205, v230, v228
	v_mul_f32_e32 v230, v228, v33
	v_sub_f32_e32 v204, v228, v230
	v_mul_f32_e32 v228, v230, v32
	v_sub_f32_e32 v203, v230, v228
	v_mul_f32_e32 v227, v219, v223
	v_mul_f32_e32 v229, v229, v227
	v_cvt_pk_bf16_f32 v176, v203, v204
	v_cvt_pk_bf16_f32 v177, v205, v206
	v_cvt_pk_bf16_f32 v178, v207, v208
	v_cvt_pk_bf16_f32 v179, v209, v210
	v_cvt_pk_bf16_f32 v180, v211, v212
	v_cvt_pk_bf16_f32 v181, v213, v214
	v_cvt_pk_bf16_f32 v182, v215, v216
	v_cvt_pk_bf16_f32 v183, v217, v218
	v_cmp_nge_f32_e32 vcc, 0x8000, v229
	s_waitcnt vmcnt(16)
	s_nop 0
	v_mfma_f32_32x32x16_bf16 v[0:15], v[112:115], v[176:179], v[0:15]
	v_mfma_f32_32x32x16_bf16 v[16:31], v[120:123], v[176:179], v[16:31]
	v_mfma_f32_32x32x16_bf16 v[0:15], v[116:119], v[180:183], v[0:15]
	v_mfma_f32_32x32x16_bf16 v[16:31], v[124:127], v[180:183], v[16:31]
	s_cmp_eq_u64 vcc, 0
	s_cbranch_scc1 .Lp6_epi
	s_cmp_eq_u32 s68, 0
	s_cbranch_scc1 .Lp6_epi
; __device__ __forceinline__ void attn_phase(const Ptrs& P, int gw, int NGW, int lane) {
;     ...
;             bf16x8 k3[4], v2[2][2];
;             { const int t3 = kt > 2 ? kt - 3 : 0, t2 = kt > 1 ? kt - 2 : 0;
; #pragma unroll
;               for (int ks = 0; ks < 4; ++ks) k3[ks] = kbase[(size_t)t3 * 256 + ks * 64];
; #pragma unroll
;               for (int dt = 0; dt < 2; ++dt)
; #pragma unroll
;                   for (int s = 0; s < 2; ++s) v2[dt][s] = vbase[(size_t)t2 * 256 + (dt * 2 + s) * 64]; }
;             f32x16 sa;
; #pragma unroll
;             for (int i = 0; i < 16; ++i) sa[i] = 0.f;
; #pragma unroll
;             for (int ks = 0; ks < 4; ++ks) sa = MFMA32(kf[ks], qf[ks], sa);
;             float beta[16], f[16];
;             const bool diag = (kt == qt);
; #pragma unroll
;             for (int i = 0; i < 16; ++i) { float ff = rcpf_(1.0f + ex2(sa[i])), bt = 1.0f - ff;
;                 if (diag) { const bool valid = crow(i, hh) < r; bt = valid ? bt : 0.0f; ff = valid ? ff : 1.0f; }
;                 beta[i] = bt; f[i] = ff; }
;             float gp[4], ot[4], pr[4];
; #pragma unroll
;             for (int g = 0; g < 4; ++g) { gp[g] = (f[4 * g] * f[4 * g + 1]) * (f[4 * g + 2] * f[4 * g + 3]);
;                 const auto rr = __builtin_amdgcn_permlane32_swap(__float_as_uint(gp[g]), __float_as_uint(gp[g]), false, false);
;                 ot[g] = __uint_as_float(rr[1]); pr[g] = __uint_as_float(rr[0]) * __uint_as_float(rr[1]); }
;             float suf = Pc; float att[16];
; #pragma unroll
;             for (int g = 3; g >= 0; --g) { float p = (hh == 0) ? suf * ot[g] : suf;
;                 att[4 * g + 3] = beta[4 * g + 3] * p; p *= f[4 * g + 3];
;                 att[4 * g + 2] = beta[4 * g + 2] * p; p *= f[4 * g + 2];
;                 att[4 * g + 1] = beta[4 * g + 1] * p; p *= f[4 * g + 1];
;                 att[4 * g] = beta[4 * g] * p;
;                 suf *= pr[g]; }
;             Pc = suf;
; #pragma unroll
;             for (int i = 0; i < 16; ++i) asm("" : "+v"(att[i]));
;             bf16x8 pf[2];
; #pragma unroll
;             for (int s = 0; s < 2; ++s) { v4u t; t.x = pk2(att[8 * s], att[8 * s + 1]); t.y = pk2(att[8 * s + 2], att[8 * s + 3]); t.z = pk2(att[8 * s + 4], att[8 * s + 5]); t.w = pk2(att[8 * s + 6], att[8 * s + 7]); pf[s] = __builtin_bit_cast(bf16x8, t); }
; #pragma unroll
	s_add_i32 s68, s68, -1
	global_load_dwordx4 v[96:99], v185, s[74:75]
	global_load_dwordx4 v[100:103], v185, s[74:75] offset:1024
	global_load_dwordx4 v[104:107], v185, s[74:75] offset:2048
	global_load_dwordx4 v[108:111], v185, s[74:75] offset:3072
	global_load_dwordx4 v[112:115], v185, s[76:77]
	global_load_dwordx4 v[116:119], v185, s[76:77] offset:1024
	global_load_dwordx4 v[120:123], v185, s[76:77] offset:2048
	global_load_dwordx4 v[124:127], v185, s[76:77] offset:3072
	s_waitcnt vmcnt(20)
	v_mfma_f32_32x32x16_bf16 v[32:47], v[128:131], v[48:51], 0
	v_mfma_f32_32x32x16_bf16 v[32:47], v[132:135], v[52:55], v[32:47]
	v_mfma_f32_32x32x16_bf16 v[32:47], v[136:139], v[56:59], v[32:47]
	v_mfma_f32_32x32x16_bf16 v[32:47], v[140:143], v[60:63], v[32:47]
	s_sub_i32 s80, s68, 3
	s_max_i32 s80, s80, 0
	s_lshl_b32 s80, s80, 12
	s_add_u32 s74, s70, s80
	s_addc_u32 s75, s71, 0
	s_add_u32 s76, s72, s80
	s_addc_u32 s77, s73, 0
	s_nop 4
	v_exp_f32_e32 v32, v32
	v_exp_f32_e32 v33, v33
	v_exp_f32_e32 v34, v34
	v_exp_f32_e32 v35, v35
	v_exp_f32_e32 v36, v36
	v_exp_f32_e32 v37, v37
	v_exp_f32_e32 v38, v38
	v_exp_f32_e32 v39, v39
	v_exp_f32_e32 v40, v40
	v_exp_f32_e32 v41, v41
	v_exp_f32_e32 v42, v42
	v_exp_f32_e32 v43, v43
	v_exp_f32_e32 v44, v44
	v_exp_f32_e32 v45, v45
	v_exp_f32_e32 v46, v46
	v_exp_f32_e32 v47, v47
	v_add_f32_e32 v32, 1.0, v32
	v_add_f32_e32 v33, 1.0, v33
	v_add_f32_e32 v34, 1.0, v34
	v_add_f32_e32 v35, 1.0, v35
	v_add_f32_e32 v36, 1.0, v36
	v_add_f32_e32 v37, 1.0, v37
	v_add_f32_e32 v38, 1.0, v38
	v_add_f32_e32 v39, 1.0, v39
	v_add_f32_e32 v40, 1.0, v40
	v_add_f32_e32 v41, 1.0, v41
	v_add_f32_e32 v42, 1.0, v42
	v_add_f32_e32 v43, 1.0, v43
	v_add_f32_e32 v44, 1.0, v44
	v_add_f32_e32 v45, 1.0, v45
	v_add_f32_e32 v46, 1.0, v46
	v_add_f32_e32 v47, 1.0, v47
	v_rcp_f32_e32 v32, v32
	v_rcp_f32_e32 v33, v33
	v_rcp_f32_e32 v34, v34
	v_rcp_f32_e32 v35, v35
	v_rcp_f32_e32 v36, v36
	v_rcp_f32_e32 v37, v37
	v_rcp_f32_e32 v38, v38
	v_rcp_f32_e32 v39, v39
	v_rcp_f32_e32 v40, v40
	v_rcp_f32_e32 v41, v41
	v_rcp_f32_e32 v42, v42
	v_rcp_f32_e32 v43, v43
	v_rcp_f32_e32 v44, v44
	v_rcp_f32_e32 v45, v45
	v_rcp_f32_e32 v46, v46
	v_rcp_f32_e32 v47, v47
	v_mul_f32_e32 v230, v32, v33
	v_mul_f32_e32 v231, v34, v35
	v_mul_f32_e32 v219, v230, v231
	v_mul_f32_e32 v230, v36, v37
	v_mul_f32_e32 v231, v38, v39
	v_mul_f32_e32 v220, v230, v231
	v_mul_f32_e32 v230, v40, v41
	v_mul_f32_e32 v231, v42, v43
	v_mul_f32_e32 v221, v230, v231
	v_mul_f32_e32 v230, v44, v45
	v_mul_f32_e32 v231, v46, v47
	v_mul_f32_e32 v222, v230, v231
	v_mov_b32_e32 v223, v219
	v_mov_b32_e32 v224, v220
	v_mov_b32_e32 v225, v221
	v_mov_b32_e32 v226, v222
	s_nop 1
	v_permlane32_swap_b32_e32 v219, v223
	v_permlane32_swap_b32_e32 v220, v224
	v_permlane32_swap_b32_e32 v221, v225
	v_permlane32_swap_b32_e32 v222, v226
	v_mul_f32_e32 v228, v229, v226
	v_cndmask_b32_e64 v228, v229, v228, s[2:3]
	v_mul_f32_e32 v230, v228, v47
	v_sub_f32_e32 v218, v228, v230
	v_mul_f32_e32 v228, v230, v46
	v_sub_f32_e32 v217, v230, v228
	v_mul_f32_e32 v230, v228, v45
	v_sub_f32_e32 v216, v228, v230
	v_mul_f32_e32 v228, v230, v44
	v_sub_f32_e32 v215, v230, v228
	v_mul_f32_e32 v227, v222, v226
	v_mul_f32_e32 v229, v229, v227
	v_mul_f32_e32 v228, v229, v225
	v_cndmask_b32_e64 v228, v229, v228, s[2:3]
	v_mul_f32_e32 v230, v228, v43
	v_sub_f32_e32 v214, v228, v230
	v_mul_f32_e32 v228, v230, v42
	v_sub_f32_e32 v213, v230, v228
	v_mul_f32_e32 v230, v228, v41
	v_sub_f32_e32 v212, v228, v230
	v_mul_f32_e32 v228, v230, v40
	v_sub_f32_e32 v211, v230, v228
	v_mul_f32_e32 v227, v221, v225
	v_mul_f32_e32 v229, v229, v227
	v_mul_f32_e32 v228, v229, v224
	v_cndmask_b32_e64 v228, v229, v228, s[2:3]
	v_mul_f32_e32 v230, v228, v39
	v_sub_f32_e32 v210, v228, v230
	v_mul_f32_e32 v228, v230, v38
	v_sub_f32_e32 v209, v230, v228
	v_mul_f32_e32 v230, v228, v37
	v_sub_f32_e32 v208, v228, v230
	v_mul_f32_e32 v228, v230, v36
	v_sub_f32_e32 v207, v230, v228
	v_mul_f32_e32 v227, v220, v224
	v_mul_f32_e32 v229, v229, v227
	v_mul_f32_e32 v228, v229, v223
	v_cndmask_b32_e64 v228, v229, v228, s[2:3]
	v_mul_f32_e32 v230, v228, v35
	v_sub_f32_e32 v206, v228, v230
	v_mul_f32_e32 v228, v230, v34
	v_sub_f32_e32 v205, v230, v228
	v_mul_f32_e32 v230, v228, v33
	v_sub_f32_e32 v204, v228, v230
	v_mul_f32_e32 v228, v230, v32
	v_sub_f32_e32 v203, v230, v228
	v_mul_f32_e32 v227, v219, v223
	v_mul_f32_e32 v229, v229, v227
	v_cvt_pk_bf16_f32 v176, v203, v204
	v_cvt_pk_bf16_f32 v177, v205, v206
	v_cvt_pk_bf16_f32 v178, v207, v208
	v_cvt_pk_bf16_f32 v179, v209, v210
	v_cvt_pk_bf16_f32 v180, v211, v212
	v_cvt_pk_bf16_f32 v181, v213, v214
	v_cvt_pk_bf16_f32 v182, v215, v216
	v_cvt_pk_bf16_f32 v183, v217, v218
	v_cmp_nge_f32_e32 vcc, 0x8000, v229
	s_waitcnt vmcnt(16)
	s_nop 0
	v_mfma_f32_32x32x16_bf16 v[0:15], v[144:147], v[176:179], v[0:15]
	v_mfma_f32_32x32x16_bf16 v[16:31], v[152:155], v[176:179], v[16:31]
	v_mfma_f32_32x32x16_bf16 v[0:15], v[148:151], v[180:183], v[0:15]
	v_mfma_f32_32x32x16_bf16 v[16:31], v[156:159], v[180:183], v[16:31]
	s_cmp_eq_u64 vcc, 0
	s_cbranch_scc1 .Lp6_epi
	s_cmp_eq_u32 s68, 0
	s_cbranch_scc1 .Lp6_epi
; __device__ __forceinline__ void attn_phase(const Ptrs& P, int gw, int NGW, int lane) {
;     ...
;             bf16x8 k3[4], v2[2][2];
;             { const int t3 = kt > 2 ? kt - 3 : 0, t2 = kt > 1 ? kt - 2 : 0;
; #pragma unroll
;               for (int ks = 0; ks < 4; ++ks) k3[ks] = kbase[(size_t)t3 * 256 + ks * 64];
; #pragma unroll
;               for (int dt = 0; dt < 2; ++dt)
; #pragma unroll
;                   for (int s = 0; s < 2; ++s) v2[dt][s] = vbase[(size_t)t2 * 256 + (dt * 2 + s) * 64]; }
;             f32x16 sa;
; #pragma unroll
;             for (int i = 0; i < 16; ++i) sa[i] = 0.f;
; #pragma unroll
;             for (int ks = 0; ks < 4; ++ks) sa = MFMA32(kf[ks], qf[ks], sa);
;             float beta[16], f[16];
;             const bool diag = (kt == qt);
; #pragma unroll
;             for (int i = 0; i < 16; ++i) { float ff = rcpf_(1.0f + ex2(sa[i])), bt = 1.0f - ff;
;                 if (diag) { const bool valid = crow(i, hh) < r; bt = valid ? bt : 0.0f; ff = valid ? ff : 1.0f; }
;                 beta[i] = bt; f[i] = ff; }
;             float gp[4], ot[4], pr[4];
; #pragma unroll
;             for (int g = 0; g < 4; ++g) { gp[g] = (f[4 * g] * f[4 * g + 1]) * (f[4 * g + 2] * f[4 * g + 3]);
;                 const auto rr = __builtin_amdgcn_permlane32_swap(__float_as_uint(gp[g]), __float_as_uint(gp[g]), false, false);
;                 ot[g] = __uint_as_float(rr[1]); pr[g] = __uint_as_float(rr[0]) * __uint_as_float(rr[1]); }
;             float suf = Pc; float att[16];
; #pragma unroll
;             for (int g = 3; g >= 0; --g) { float p = (hh == 0) ? suf * ot[g] : suf;
;                 att[4 * g + 3] = beta[4 * g + 3] * p; p *= f[4 * g + 3];
;                 att[4 * g + 2] = beta[4 * g + 2] * p; p *= f[4 * g + 2];
;                 att[4 * g + 1] = beta[4 * g + 1] * p; p *= f[4 * g + 1];
;                 att[4 * g] = beta[4 * g] * p;
;                 suf *= pr[g]; }
;             Pc = suf;
; #pragma unroll
;             for (int i = 0; i < 16; ++i) asm("" : "+v"(att[i]));
;             bf16x8 pf[2];
; #pragma unroll
;             for (int s = 0; s < 2; ++s) { v4u t; t.x = pk2(att[8 * s], att[8 * s + 1]); t.y = pk2(att[8 * s + 2], att[8 * s + 3]); t.z = pk2(att[8 * s + 4], att[8 * s + 5]); t.w = pk2(att[8 * s + 6], att[8 * s + 7]); pf[s] = __builtin_bit_cast(bf16x8, t); }
; #pragma unroll
	s_add_i32 s68, s68, -1
	global_load_dwordx4 v[128:131], v185, s[74:75]
	global_load_dwordx4 v[132:135], v185, s[74:75] offset:1024
	global_load_dwordx4 v[136:139], v185, s[74:75] offset:2048
	global_load_dwordx4 v[140:143], v185, s[74:75] offset:3072
	global_load_dwordx4 v[144:147], v185, s[76:77]
	global_load_dwordx4 v[148:151], v185, s[76:77] offset:1024
	global_load_dwordx4 v[152:155], v185, s[76:77] offset:2048
	global_load_dwordx4 v[156:159], v185, s[76:77] offset:3072
	s_waitcnt vmcnt(20)
	v_mfma_f32_32x32x16_bf16 v[32:47], v[64:67], v[48:51], 0
	v_mfma_f32_32x32x16_bf16 v[32:47], v[68:71], v[52:55], v[32:47]
	v_mfma_f32_32x32x16_bf16 v[32:47], v[72:75], v[56:59], v[32:47]
	v_mfma_f32_32x32x16_bf16 v[32:47], v[76:79], v[60:63], v[32:47]
	s_sub_i32 s80, s68, 3
	s_max_i32 s80, s80, 0
	s_lshl_b32 s80, s80, 12
	s_add_u32 s74, s70, s80
	s_addc_u32 s75, s71, 0
	s_add_u32 s76, s72, s80
	s_addc_u32 s77, s73, 0
	s_nop 4
	v_exp_f32_e32 v32, v32
	v_exp_f32_e32 v33, v33
	v_exp_f32_e32 v34, v34
	v_exp_f32_e32 v35, v35
	v_exp_f32_e32 v36, v36
	v_exp_f32_e32 v37, v37
	v_exp_f32_e32 v38, v38
	v_exp_f32_e32 v39, v39
	v_exp_f32_e32 v40, v40
	v_exp_f32_e32 v41, v41
	v_exp_f32_e32 v42, v42
	v_exp_f32_e32 v43, v43
	v_exp_f32_e32 v44, v44
	v_exp_f32_e32 v45, v45
	v_exp_f32_e32 v46, v46
	v_exp_f32_e32 v47, v47
	v_add_f32_e32 v32, 1.0, v32
	v_add_f32_e32 v33, 1.0, v33
	v_add_f32_e32 v34, 1.0, v34
	v_add_f32_e32 v35, 1.0, v35
	v_add_f32_e32 v36, 1.0, v36
	v_add_f32_e32 v37, 1.0, v37
	v_add_f32_e32 v38, 1.0, v38
	v_add_f32_e32 v39, 1.0, v39
	v_add_f32_e32 v40, 1.0, v40
	v_add_f32_e32 v41, 1.0, v41
	v_add_f32_e32 v42, 1.0, v42
	v_add_f32_e32 v43, 1.0, v43
	v_add_f32_e32 v44, 1.0, v44
	v_add_f32_e32 v45, 1.0, v45
	v_add_f32_e32 v46, 1.0, v46
	v_add_f32_e32 v47, 1.0, v47
	v_rcp_f32_e32 v32, v32
	v_rcp_f32_e32 v33, v33
	v_rcp_f32_e32 v34, v34
	v_rcp_f32_e32 v35, v35
	v_rcp_f32_e32 v36, v36
	v_rcp_f32_e32 v37, v37
	v_rcp_f32_e32 v38, v38
	v_rcp_f32_e32 v39, v39
	v_rcp_f32_e32 v40, v40
	v_rcp_f32_e32 v41, v41
	v_rcp_f32_e32 v42, v42
	v_rcp_f32_e32 v43, v43
	v_rcp_f32_e32 v44, v44
	v_rcp_f32_e32 v45, v45
	v_rcp_f32_e32 v46, v46
	v_rcp_f32_e32 v47, v47
	v_mul_f32_e32 v230, v32, v33
	v_mul_f32_e32 v231, v34, v35
	v_mul_f32_e32 v219, v230, v231
	v_mul_f32_e32 v230, v36, v37
	v_mul_f32_e32 v231, v38, v39
	v_mul_f32_e32 v220, v230, v231
	v_mul_f32_e32 v230, v40, v41
	v_mul_f32_e32 v231, v42, v43
	v_mul_f32_e32 v221, v230, v231
	v_mul_f32_e32 v230, v44, v45
	v_mul_f32_e32 v231, v46, v47
	v_mul_f32_e32 v222, v230, v231
	v_mov_b32_e32 v223, v219
	v_mov_b32_e32 v224, v220
	v_mov_b32_e32 v225, v221
	v_mov_b32_e32 v226, v222
	s_nop 1
	v_permlane32_swap_b32_e32 v219, v223
	v_permlane32_swap_b32_e32 v220, v224
	v_permlane32_swap_b32_e32 v221, v225
	v_permlane32_swap_b32_e32 v222, v226
	v_mul_f32_e32 v228, v229, v226
	v_cndmask_b32_e64 v228, v229, v228, s[2:3]
	v_mul_f32_e32 v230, v228, v47
	v_sub_f32_e32 v218, v228, v230
	v_mul_f32_e32 v228, v230, v46
	v_sub_f32_e32 v217, v230, v228
	v_mul_f32_e32 v230, v228, v45
	v_sub_f32_e32 v216, v228, v230
	v_mul_f32_e32 v228, v230, v44
	v_sub_f32_e32 v215, v230, v228
	v_mul_f32_e32 v227, v222, v226
	v_mul_f32_e32 v229, v229, v227
	v_mul_f32_e32 v228, v229, v225
	v_cndmask_b32_e64 v228, v229, v228, s[2:3]
	v_mul_f32_e32 v230, v228, v43
	v_sub_f32_e32 v214, v228, v230
	v_mul_f32_e32 v228, v230, v42
	v_sub_f32_e32 v213, v230, v228
	v_mul_f32_e32 v230, v228, v41
	v_sub_f32_e32 v212, v228, v230
	v_mul_f32_e32 v228, v230, v40
	v_sub_f32_e32 v211, v230, v228
	v_mul_f32_e32 v227, v221, v225
	v_mul_f32_e32 v229, v229, v227
	v_mul_f32_e32 v228, v229, v224
	v_cndmask_b32_e64 v228, v229, v228, s[2:3]
	v_mul_f32_e32 v230, v228, v39
	v_sub_f32_e32 v210, v228, v230
	v_mul_f32_e32 v228, v230, v38
	v_sub_f32_e32 v209, v230, v228
	v_mul_f32_e32 v230, v228, v37
	v_sub_f32_e32 v208, v228, v230
	v_mul_f32_e32 v228, v230, v36
	v_sub_f32_e32 v207, v230, v228
	v_mul_f32_e32 v227, v220, v224
	v_mul_f32_e32 v229, v229, v227
	v_mul_f32_e32 v228, v229, v223
	v_cndmask_b32_e64 v228, v229, v228, s[2:3]
	v_mul_f32_e32 v230, v228, v35
	v_sub_f32_e32 v206, v228, v230
	v_mul_f32_e32 v228, v230, v34
	v_sub_f32_e32 v205, v230, v228
	v_mul_f32_e32 v230, v228, v33
	v_sub_f32_e32 v204, v228, v230
	v_mul_f32_e32 v228, v230, v32
	v_sub_f32_e32 v203, v230, v228
	v_mul_f32_e32 v227, v219, v223
	v_mul_f32_e32 v229, v229, v227
	v_cvt_pk_bf16_f32 v176, v203, v204
	v_cvt_pk_bf16_f32 v177, v205, v206
	v_cvt_pk_bf16_f32 v178, v207, v208
	v_cvt_pk_bf16_f32 v179, v209, v210
	v_cvt_pk_bf16_f32 v180, v211, v212
	v_cvt_pk_bf16_f32 v181, v213, v214
	v_cvt_pk_bf16_f32 v182, v215, v216
	v_cvt_pk_bf16_f32 v183, v217, v218
	v_cmp_nge_f32_e32 vcc, 0x8000, v229
	s_waitcnt vmcnt(16)
	s_nop 0
	v_mfma_f32_32x32x16_bf16 v[0:15], v[80:83], v[176:179], v[0:15]
	v_mfma_f32_32x32x16_bf16 v[16:31], v[88:91], v[176:179], v[16:31]
	v_mfma_f32_32x32x16_bf16 v[0:15], v[84:87], v[180:183], v[0:15]
	v_mfma_f32_32x32x16_bf16 v[16:31], v[92:95], v[180:183], v[16:31]
	s_cmp_eq_u64 vcc, 0
	s_cbranch_scc1 .Lp6_epi
	s_cmp_eq_u32 s68, 0
	s_cbranch_scc1 .Lp6_epi
	s_add_i32 s68, s68, -1
	global_load_dwordx4 v[64:67], v185, s[74:75]
	global_load_dwordx4 v[68:71], v185, s[74:75] offset:1024
	global_load_dwordx4 v[72:75], v185, s[74:75] offset:2048
	global_load_dwordx4 v[76:79], v185, s[74:75] offset:3072
	global_load_dwordx4 v[80:83], v185, s[76:77]
	global_load_dwordx4 v[84:87], v185, s[76:77] offset:1024
	global_load_dwordx4 v[88:91], v185, s[76:77] offset:2048
	global_load_dwordx4 v[92:95], v185, s[76:77] offset:3072
	s_branch .Lp6_loop
; __device__ __forceinline__ unsigned pk2(float lo, float hi) { f32x2_t v = {lo, hi}; bf16x2_t b = __builtin_convertvector(v, bf16x2_t); return __builtin_bit_cast(unsigned, b); }
; __device__ __forceinline__ float bflo(unsigned u) { return __uint_as_float(u << 16); }
; __device__ __forceinline__ float bfhi(unsigned u) { return __uint_as_float(u & 0xffff0000u); }
; __device__ __forceinline__ float sigmoid_(float x) { return rcpf_(1.0f + ex2(-LOG2E * x)); }
; __device__ __forceinline__ void attn_phase(const Ptrs& P, int gw, int NGW, int lane) {
;     ...
;         const size_t row = rowbase + qt * 32 + r;
;         bf16* op = OG + row * AW + h * HD + 8 * hh;
; #pragma unroll
;         for (int dt = 0; dt < 2; ++dt)
; #pragma unroll
;             for (int g = 0; g < 4; g += 2) { v2u pk[2];
; #pragma unroll
;                 for (int e = 0; e < 2; ++e) { const v2u graw = gq_[dt * 4 + g + e]; const int i0 = 4 * (g + e);
;                     const float g0 = bflo(graw.x), g1 = bfhi(graw.x), g2 = bflo(graw.y), g3 = bfhi(graw.y);
;                     const float v0 = dt ? o1[i0] : o0[i0], v1 = dt ? o1[i0 + 1] : o0[i0 + 1], v2 = dt ? o1[i0 + 2] : o0[i0 + 2], v3 = dt ? o1[i0 + 3] : o0[i0 + 3];
;                     float w0 = v0 * (g0 * sigmoid_(g0)), w1 = v1 * (g1 * sigmoid_(g1)), w2 = v2 * (g2 * sigmoid_(g2)), w3 = v3 * (g3 * sigmoid_(g3));
;                     asm("" : "+v"(w0)); asm("" : "+v"(w1)); asm("" : "+v"(w2)); asm("" : "+v"(w3));
;                     pk[e].x = pk2(w0, w1); pk[e].y = pk2(w2, w3); }
;                 const auto rx = __builtin_amdgcn_permlane32_swap(pk[0].x, pk[1].x, false, false), ry = __builtin_amdgcn_permlane32_swap(pk[0].y, pk[1].y, false, false);
;                 const v4u o = {rx[0], ry[0], rx[1], ry[1]};
;                 *(v4u*)(op + dt * 32 + 8 * g) = o; }
.Lp6_epi:
	s_lshr_b32 s80, s69, 4
	s_lshl_b32 s80, s80, 12
	s_lshl_b32 s81, s63, 5
	s_or_b32 s80, s80, s81
	v_or_b32_e32 v239, s80, v234
	v_lshlrev_b32_e32 v239, 11, v239
	s_and_b32 s81, s69, 15
	s_lshl_b32 s81, s81, 7
	v_add3_u32 v239, v239, s81, v238
	s_add_i32 s58, s58, s62
	s_cmpk_lt_i32 s58, 0x2000
	s_cselect_b32 s82, 1, 0
	s_waitcnt vmcnt(16)
	v_mov_b32_e32 v187, v160
	v_mov_b32_e32 v188, v161
	v_mov_b32_e32 v189, v162
	v_mov_b32_e32 v190, v163
	v_mov_b32_e32 v191, v164
	v_mov_b32_e32 v192, v165
	v_mov_b32_e32 v193, v166
	v_mov_b32_e32 v194, v167
	v_mov_b32_e32 v195, v168
	v_mov_b32_e32 v196, v169
	v_mov_b32_e32 v197, v170
	v_mov_b32_e32 v198, v171
	v_mov_b32_e32 v199, v172
	v_mov_b32_e32 v200, v173
	v_mov_b32_e32 v201, v174
	v_mov_b32_e32 v202, v175
	s_cmp_eq_u32 s82, 0
	s_cbranch_scc1 .Lp6_epi_compute
	s_and_b32 s63, s58, 0x7f
	s_lshr_b32 s69, s58, 7
	s_lshl_b32 s78, s58, 12
	s_add_u32 s74, s44, s78
	s_addc_u32 s75, s45, 0
	s_add_u32 s76, s50, s78
	s_addc_u32 s77, s51, 0
	global_load_dwordx4 v[48:51], v185, s[74:75]
	global_load_dwordx4 v[52:55], v185, s[74:75] offset:1024
	global_load_dwordx4 v[56:59], v185, s[74:75] offset:2048
	global_load_dwordx4 v[60:63], v185, s[74:75] offset:3072
	global_load_dwordx2 v[160:161], v233, s[76:77]
	global_load_dwordx2 v[162:163], v233, s[76:77] offset:512
	global_load_dwordx2 v[164:165], v233, s[76:77] offset:1024
	global_load_dwordx2 v[166:167], v233, s[76:77] offset:1536
	global_load_dwordx2 v[168:169], v233, s[76:77] offset:2048
	global_load_dwordx2 v[170:171], v233, s[76:77] offset:2560
	global_load_dwordx2 v[172:173], v233, s[76:77] offset:3072
	global_load_dwordx2 v[174:175], v233, s[76:77] offset:3584
	s_lshl_b32 s78, s69, 19
	s_add_u32 s70, s46, s78
	s_addc_u32 s71, s47, 0
	s_add_u32 s72, s48, s78
	s_addc_u32 s73, s49, 0
	s_lshl_b32 s78, s63, 12
	s_add_u32 s74, s70, s78
	s_addc_u32 s75, s71, 0
	s_add_u32 s76, s72, s78
	s_addc_u32 s77, s73, 0
	global_load_dwordx4 v[64:67], v185, s[74:75]
	global_load_dwordx4 v[68:71], v185, s[74:75] offset:1024
	global_load_dwordx4 v[72:75], v185, s[74:75] offset:2048
	global_load_dwordx4 v[76:79], v185, s[74:75] offset:3072
	global_load_dwordx4 v[80:83], v185, s[76:77]
	global_load_dwordx4 v[84:87], v185, s[76:77] offset:1024
	global_load_dwordx4 v[88:91], v185, s[76:77] offset:2048
	global_load_dwordx4 v[92:95], v185, s[76:77] offset:3072
	s_sub_i32 s78, s63, 1
	s_max_i32 s78, s78, 0
	s_lshl_b32 s78, s78, 12
	s_add_u32 s74, s70, s78
	s_addc_u32 s75, s71, 0
	s_add_u32 s76, s72, s78
	s_addc_u32 s77, s73, 0
	global_load_dwordx4 v[96:99], v185, s[74:75]
	global_load_dwordx4 v[100:103], v185, s[74:75] offset:1024
	global_load_dwordx4 v[104:107], v185, s[74:75] offset:2048
	global_load_dwordx4 v[108:111], v185, s[74:75] offset:3072
	global_load_dwordx4 v[112:115], v185, s[76:77]
	global_load_dwordx4 v[116:119], v185, s[76:77] offset:1024
	global_load_dwordx4 v[120:123], v185, s[76:77] offset:2048
	global_load_dwordx4 v[124:127], v185, s[76:77] offset:3072
	s_sub_i32 s78, s63, 2
	s_max_i32 s78, s78, 0
	s_lshl_b32 s78, s78, 12
	s_add_u32 s74, s70, s78
	s_addc_u32 s75, s71, 0
	s_add_u32 s76, s72, s78
	s_addc_u32 s77, s73, 0
	global_load_dwordx4 v[128:131], v185, s[74:75]
	global_load_dwordx4 v[132:135], v185, s[74:75] offset:1024
	global_load_dwordx4 v[136:139], v185, s[74:75] offset:2048
	global_load_dwordx4 v[140:143], v185, s[74:75] offset:3072
	global_load_dwordx4 v[144:147], v185, s[76:77]
	global_load_dwordx4 v[148:151], v185, s[76:77] offset:1024
	global_load_dwordx4 v[152:155], v185, s[76:77] offset:2048
	global_load_dwordx4 v[156:159], v185, s[76:77] offset:3072
.Lp6_epi_compute:
	v_lshlrev_b32_e32 v240, 16, v187
	v_and_b32_e32 v241, 0xffff0000, v187
	v_lshlrev_b32_e32 v242, 16, v188
	v_and_b32_e32 v243, 0xffff0000, v188
	v_mul_f32_e32 v244, 0xbfb8aa3b, v240
	v_mul_f32_e32 v245, 0xbfb8aa3b, v241
	v_mul_f32_e32 v246, 0xbfb8aa3b, v242
	v_mul_f32_e32 v247, 0xbfb8aa3b, v243
	v_exp_f32_e32 v244, v244
	v_exp_f32_e32 v245, v245
	v_exp_f32_e32 v246, v246
	v_exp_f32_e32 v247, v247
	v_add_f32_e32 v244, 1.0, v244
	v_add_f32_e32 v245, 1.0, v245
	v_add_f32_e32 v246, 1.0, v246
	v_add_f32_e32 v247, 1.0, v247
	v_rcp_f32_e32 v244, v244
	v_rcp_f32_e32 v245, v245
	v_rcp_f32_e32 v246, v246
	v_rcp_f32_e32 v247, v247
	v_mul_f32_e32 v240, v244, v240
	v_mul_f32_e32 v241, v245, v241
	v_mul_f32_e32 v242, v246, v242
	v_mul_f32_e32 v243, v247, v243
	v_mul_f32_e32 v240, v240, v0
	v_mul_f32_e32 v241, v241, v1
	v_mul_f32_e32 v242, v242, v2
	v_mul_f32_e32 v243, v243, v3
	v_cvt_pk_bf16_f32 v248, v240, v241
	v_cvt_pk_bf16_f32 v249, v242, v243
	v_lshlrev_b32_e32 v240, 16, v189
	v_and_b32_e32 v241, 0xffff0000, v189
	v_lshlrev_b32_e32 v242, 16, v190
	v_and_b32_e32 v243, 0xffff0000, v190
	v_mul_f32_e32 v244, 0xbfb8aa3b, v240
	v_mul_f32_e32 v245, 0xbfb8aa3b, v241
	v_mul_f32_e32 v246, 0xbfb8aa3b, v242
	v_mul_f32_e32 v247, 0xbfb8aa3b, v243
	v_exp_f32_e32 v244, v244
	v_exp_f32_e32 v245, v245
	v_exp_f32_e32 v246, v246
	v_exp_f32_e32 v247, v247
	v_add_f32_e32 v244, 1.0, v244
	v_add_f32_e32 v245, 1.0, v245
	v_add_f32_e32 v246, 1.0, v246
	v_add_f32_e32 v247, 1.0, v247
	v_rcp_f32_e32 v244, v244
	v_rcp_f32_e32 v245, v245
	v_rcp_f32_e32 v246, v246
	v_rcp_f32_e32 v247, v247
	v_mul_f32_e32 v240, v244, v240
	v_mul_f32_e32 v241, v245, v241
	v_mul_f32_e32 v242, v246, v242
	v_mul_f32_e32 v243, v247, v243
	v_mul_f32_e32 v240, v240, v4
	v_mul_f32_e32 v241, v241, v5
	v_mul_f32_e32 v242, v242, v6
	v_mul_f32_e32 v243, v243, v7
	v_cvt_pk_bf16_f32 v250, v240, v241
	v_cvt_pk_bf16_f32 v251, v242, v243
	s_nop 1
	v_permlane32_swap_b32_e32 v248, v250
	v_permlane32_swap_b32_e32 v249, v251
	global_store_dwordx4 v239, v[248:251], s[42:43]
; __device__ __forceinline__ unsigned pk2(float lo, float hi) { f32x2_t v = {lo, hi}; bf16x2_t b = __builtin_convertvector(v, bf16x2_t); return __builtin_bit_cast(unsigned, b); }
; __device__ __forceinline__ float bflo(unsigned u) { return __uint_as_float(u << 16); }
; __device__ __forceinline__ float bfhi(unsigned u) { return __uint_as_float(u & 0xffff0000u); }
; __device__ __forceinline__ float sigmoid_(float x) { return rcpf_(1.0f + ex2(-LOG2E * x)); }
; __device__ __forceinline__ void attn_phase(const Ptrs& P, int gw, int NGW, int lane) {
;     ...
; #pragma unroll
;         for (int dt = 0; dt < 2; ++dt)
; #pragma unroll
;             for (int g = 0; g < 4; g += 2) { v2u pk[2];
; #pragma unroll
;                 for (int e = 0; e < 2; ++e) { const v2u graw = gq_[dt * 4 + g + e]; const int i0 = 4 * (g + e);
;                     const float g0 = bflo(graw.x), g1 = bfhi(graw.x), g2 = bflo(graw.y), g3 = bfhi(graw.y);
;                     const float v0 = dt ? o1[i0] : o0[i0], v1 = dt ? o1[i0 + 1] : o0[i0 + 1], v2 = dt ? o1[i0 + 2] : o0[i0 + 2], v3 = dt ? o1[i0 + 3] : o0[i0 + 3];
;                     float w0 = v0 * (g0 * sigmoid_(g0)), w1 = v1 * (g1 * sigmoid_(g1)), w2 = v2 * (g2 * sigmoid_(g2)), w3 = v3 * (g3 * sigmoid_(g3));
;                     asm("" : "+v"(w0)); asm("" : "+v"(w1)); asm("" : "+v"(w2)); asm("" : "+v"(w3));
;                     pk[e].x = pk2(w0, w1); pk[e].y = pk2(w2, w3); }
;                 const auto rx = __builtin_amdgcn_permlane32_swap(pk[0].x, pk[1].x, false, false), ry = __builtin_amdgcn_permlane32_swap(pk[0].y, pk[1].y, false, false);
;                 const v4u o = {rx[0], ry[0], rx[1], ry[1]};
;                 *(v4u*)(op + dt * 32 + 8 * g) = o; }
	s_nop 1
	v_lshlrev_b32_e32 v240, 16, v191
	v_and_b32_e32 v241, 0xffff0000, v191
	v_lshlrev_b32_e32 v242, 16, v192
	v_and_b32_e32 v243, 0xffff0000, v192
	v_mul_f32_e32 v244, 0xbfb8aa3b, v240
	v_mul_f32_e32 v245, 0xbfb8aa3b, v241
	v_mul_f32_e32 v246, 0xbfb8aa3b, v242
	v_mul_f32_e32 v247, 0xbfb8aa3b, v243
	v_exp_f32_e32 v244, v244
	v_exp_f32_e32 v245, v245
	v_exp_f32_e32 v246, v246
	v_exp_f32_e32 v247, v247
	v_add_f32_e32 v244, 1.0, v244
	v_add_f32_e32 v245, 1.0, v245
	v_add_f32_e32 v246, 1.0, v246
	v_add_f32_e32 v247, 1.0, v247
	v_rcp_f32_e32 v244, v244
	v_rcp_f32_e32 v245, v245
	v_rcp_f32_e32 v246, v246
	v_rcp_f32_e32 v247, v247
	v_mul_f32_e32 v240, v244, v240
	v_mul_f32_e32 v241, v245, v241
	v_mul_f32_e32 v242, v246, v242
	v_mul_f32_e32 v243, v247, v243
	v_mul_f32_e32 v240, v240, v8
	v_mul_f32_e32 v241, v241, v9
	v_mul_f32_e32 v242, v242, v10
	v_mul_f32_e32 v243, v243, v11
	v_cvt_pk_bf16_f32 v248, v240, v241
	v_cvt_pk_bf16_f32 v249, v242, v243
	v_lshlrev_b32_e32 v240, 16, v193
	v_and_b32_e32 v241, 0xffff0000, v193
	v_lshlrev_b32_e32 v242, 16, v194
	v_and_b32_e32 v243, 0xffff0000, v194
	v_mul_f32_e32 v244, 0xbfb8aa3b, v240
	v_mul_f32_e32 v245, 0xbfb8aa3b, v241
	v_mul_f32_e32 v246, 0xbfb8aa3b, v242
	v_mul_f32_e32 v247, 0xbfb8aa3b, v243
	v_exp_f32_e32 v244, v244
	v_exp_f32_e32 v245, v245
	v_exp_f32_e32 v246, v246
	v_exp_f32_e32 v247, v247
	v_add_f32_e32 v244, 1.0, v244
	v_add_f32_e32 v245, 1.0, v245
	v_add_f32_e32 v246, 1.0, v246
	v_add_f32_e32 v247, 1.0, v247
	v_rcp_f32_e32 v244, v244
	v_rcp_f32_e32 v245, v245
	v_rcp_f32_e32 v246, v246
	v_rcp_f32_e32 v247, v247
	v_mul_f32_e32 v240, v244, v240
	v_mul_f32_e32 v241, v245, v241
	v_mul_f32_e32 v242, v246, v242
	v_mul_f32_e32 v243, v247, v243
	v_mul_f32_e32 v240, v240, v12
	v_mul_f32_e32 v241, v241, v13
	v_mul_f32_e32 v242, v242, v14
	v_mul_f32_e32 v243, v243, v15
	v_cvt_pk_bf16_f32 v250, v240, v241
	v_cvt_pk_bf16_f32 v251, v242, v243
	s_nop 1
	v_permlane32_swap_b32_e32 v248, v250
	v_permlane32_swap_b32_e32 v249, v251
	global_store_dwordx4 v239, v[248:251], s[42:43] offset:32
	s_nop 1
	v_lshlrev_b32_e32 v240, 16, v195
	v_and_b32_e32 v241, 0xffff0000, v195
	v_lshlrev_b32_e32 v242, 16, v196
	v_and_b32_e32 v243, 0xffff0000, v196
	v_mul_f32_e32 v244, 0xbfb8aa3b, v240
	v_mul_f32_e32 v245, 0xbfb8aa3b, v241
	v_mul_f32_e32 v246, 0xbfb8aa3b, v242
	v_mul_f32_e32 v247, 0xbfb8aa3b, v243
	v_exp_f32_e32 v244, v244
	v_exp_f32_e32 v245, v245
	v_exp_f32_e32 v246, v246
	v_exp_f32_e32 v247, v247
	v_add_f32_e32 v244, 1.0, v244
	v_add_f32_e32 v245, 1.0, v245
	v_add_f32_e32 v246, 1.0, v246
	v_add_f32_e32 v247, 1.0, v247
	v_rcp_f32_e32 v244, v244
	v_rcp_f32_e32 v245, v245
	v_rcp_f32_e32 v246, v246
	v_rcp_f32_e32 v247, v247
	v_mul_f32_e32 v240, v244, v240
	v_mul_f32_e32 v241, v245, v241
	v_mul_f32_e32 v242, v246, v242
	v_mul_f32_e32 v243, v247, v243
	v_mul_f32_e32 v240, v240, v16
	v_mul_f32_e32 v241, v241, v17
	v_mul_f32_e32 v242, v242, v18
	v_mul_f32_e32 v243, v243, v19
	v_cvt_pk_bf16_f32 v248, v240, v241
	v_cvt_pk_bf16_f32 v249, v242, v243
	v_lshlrev_b32_e32 v240, 16, v197
	v_and_b32_e32 v241, 0xffff0000, v197
	v_lshlrev_b32_e32 v242, 16, v198
	v_and_b32_e32 v243, 0xffff0000, v198
	v_mul_f32_e32 v244, 0xbfb8aa3b, v240
	v_mul_f32_e32 v245, 0xbfb8aa3b, v241
	v_mul_f32_e32 v246, 0xbfb8aa3b, v242
	v_mul_f32_e32 v247, 0xbfb8aa3b, v243
	v_exp_f32_e32 v244, v244
	v_exp_f32_e32 v245, v245
	v_exp_f32_e32 v246, v246
	v_exp_f32_e32 v247, v247
	v_add_f32_e32 v244, 1.0, v244
	v_add_f32_e32 v245, 1.0, v245
	v_add_f32_e32 v246, 1.0, v246
	v_add_f32_e32 v247, 1.0, v247
	v_rcp_f32_e32 v244, v244
	v_rcp_f32_e32 v245, v245
	v_rcp_f32_e32 v246, v246
	v_rcp_f32_e32 v247, v247
	v_mul_f32_e32 v240, v244, v240
	v_mul_f32_e32 v241, v245, v241
	v_mul_f32_e32 v242, v246, v242
	v_mul_f32_e32 v243, v247, v243
	v_mul_f32_e32 v240, v240, v20
	v_mul_f32_e32 v241, v241, v21
	v_mul_f32_e32 v242, v242, v22
	v_mul_f32_e32 v243, v243, v23
	v_cvt_pk_bf16_f32 v250, v240, v241
	v_cvt_pk_bf16_f32 v251, v242, v243
	s_nop 1
	v_permlane32_swap_b32_e32 v248, v250
	v_permlane32_swap_b32_e32 v249, v251
	global_store_dwordx4 v239, v[248:251], s[42:43] offset:64
	s_nop 1
	v_lshlrev_b32_e32 v240, 16, v199
	v_and_b32_e32 v241, 0xffff0000, v199
	v_lshlrev_b32_e32 v242, 16, v200
	v_and_b32_e32 v243, 0xffff0000, v200
	v_mul_f32_e32 v244, 0xbfb8aa3b, v240
	v_mul_f32_e32 v245, 0xbfb8aa3b, v241
	v_mul_f32_e32 v246, 0xbfb8aa3b, v242
	v_mul_f32_e32 v247, 0xbfb8aa3b, v243
	v_exp_f32_e32 v244, v244
	v_exp_f32_e32 v245, v245
	v_exp_f32_e32 v246, v246
	v_exp_f32_e32 v247, v247
	v_add_f32_e32 v244, 1.0, v244
	v_add_f32_e32 v245, 1.0, v245
	v_add_f32_e32 v246, 1.0, v246
	v_add_f32_e32 v247, 1.0, v247
	v_rcp_f32_e32 v244, v244
	v_rcp_f32_e32 v245, v245
	v_rcp_f32_e32 v246, v246
	v_rcp_f32_e32 v247, v247
	v_mul_f32_e32 v240, v244, v240
	v_mul_f32_e32 v241, v245, v241
	v_mul_f32_e32 v242, v246, v242
	v_mul_f32_e32 v243, v247, v243
	v_mul_f32_e32 v240, v240, v24
	v_mul_f32_e32 v241, v241, v25
	v_mul_f32_e32 v242, v242, v26
	v_mul_f32_e32 v243, v243, v27
	v_cvt_pk_bf16_f32 v248, v240, v241
	v_cvt_pk_bf16_f32 v249, v242, v243
	v_lshlrev_b32_e32 v240, 16, v201
	v_and_b32_e32 v241, 0xffff0000, v201
	v_lshlrev_b32_e32 v242, 16, v202
	v_and_b32_e32 v243, 0xffff0000, v202
	v_mul_f32_e32 v244, 0xbfb8aa3b, v240
	v_mul_f32_e32 v245, 0xbfb8aa3b, v241
	v_mul_f32_e32 v246, 0xbfb8aa3b, v242
	v_mul_f32_e32 v247, 0xbfb8aa3b, v243
	v_exp_f32_e32 v244, v244
	v_exp_f32_e32 v245, v245
	v_exp_f32_e32 v246, v246
	v_exp_f32_e32 v247, v247
	v_add_f32_e32 v244, 1.0, v244
	v_add_f32_e32 v245, 1.0, v245
	v_add_f32_e32 v246, 1.0, v246
	v_add_f32_e32 v247, 1.0, v247
	v_rcp_f32_e32 v244, v244
	v_rcp_f32_e32 v245, v245
	v_rcp_f32_e32 v246, v246
	v_rcp_f32_e32 v247, v247
	v_mul_f32_e32 v240, v244, v240
	v_mul_f32_e32 v241, v245, v241
	v_mul_f32_e32 v242, v246, v242
	v_mul_f32_e32 v243, v247, v243
	v_mul_f32_e32 v240, v240, v28
	v_mul_f32_e32 v241, v241, v29
	v_mul_f32_e32 v242, v242, v30
	v_mul_f32_e32 v243, v243, v31
	v_cvt_pk_bf16_f32 v250, v240, v241
	v_cvt_pk_bf16_f32 v251, v242, v243
	s_nop 1
	v_permlane32_swap_b32_e32 v248, v250
	v_permlane32_swap_b32_e32 v249, v251
	global_store_dwordx4 v239, v[248:251], s[42:43] offset:96
	s_nop 1
	s_cmp_lg_u32 s82, 0
	s_cbranch_scc1 .Lp6_unit

; __global__ void __launch_bounds__(NT, 2) trunk_fwd(Args args) {
;     extern __shared__ __attribute__((aligned(16))) unsigned char lds_raw[];
	.amdhsa_kernel _Z9trunk_fwd4Args
		.amdhsa_group_segment_fixed_size 0
		.amdhsa_private_segment_fixed_size 0
		.amdhsa_kernarg_size 384
		.amdhsa_user_sgpr_count 2
		.amdhsa_user_sgpr_dispatch_ptr 0
		.amdhsa_user_sgpr_queue_ptr 0
		.amdhsa_user_sgpr_kernarg_segment_ptr 1
		.amdhsa_user_sgpr_dispatch_id 0
		.amdhsa_user_sgpr_kernarg_preload_length 0
		.amdhsa_user_sgpr_kernarg_preload_offset 0
		.amdhsa_user_sgpr_private_segment_size 0
		.amdhsa_uses_dynamic_stack 0
		.amdhsa_enable_private_segment 0
		.amdhsa_system_sgpr_workgroup_id_x 1
		.amdhsa_system_sgpr_workgroup_id_y 0
		.amdhsa_system_sgpr_workgroup_id_z 0
		.amdhsa_system_sgpr_workgroup_info 0
		.amdhsa_system_vgpr_workitem_id 2
		.amdhsa_next_free_vgpr 252
		.amdhsa_next_free_sgpr 95
		.amdhsa_accum_offset 252
		.amdhsa_reserve_vcc 1
		.amdhsa_float_round_mode_32 0
		.amdhsa_float_round_mode_16_64 0
		.amdhsa_float_denorm_mode_32 3
		.amdhsa_float_denorm_mode_16_64 3
		.amdhsa_dx10_clamp 1
		.amdhsa_ieee_mode 1
		.amdhsa_fp16_overflow 0
		.amdhsa_tg_split 0
		.amdhsa_exception_fp_ieee_invalid_op 0
		.amdhsa_exception_fp_denorm_src 0
		.amdhsa_exception_fp_ieee_div_zero 0
		.amdhsa_exception_fp_ieee_overflow 0
		.amdhsa_exception_fp_ieee_underflow 0
		.amdhsa_exception_fp_ieee_inexact 0
		.amdhsa_exception_int_div_zero 0
	.end_amdhsa_kernel

; __global__ void __launch_bounds__(NT, 2) trunk_fwd(Args args) {
;     extern __shared__ __attribute__((aligned(16))) unsigned char lds_raw[];
amdhsa.kernels:
  - .agpr_count:     0
    .args:
      - .offset:         0
        .size:           128
        .value_kind:     by_value
      - .offset:         128
        .size:           4
        .value_kind:     hidden_block_count_x
      - .offset:         132
        .size:           4
        .value_kind:     hidden_block_count_y
      - .offset:         136
        .size:           4
        .value_kind:     hidden_block_count_z
      - .offset:         140
        .size:           2
        .value_kind:     hidden_group_size_x
      - .offset:         142
        .size:           2
        .value_kind:     hidden_group_size_y
      - .offset:         144
        .size:           2
        .value_kind:     hidden_group_size_z
      - .offset:         146
        .size:           2
        .value_kind:     hidden_remainder_x
      - .offset:         148
        .size:           2
        .value_kind:     hidden_remainder_y
      - .offset:         150
        .size:           2
        .value_kind:     hidden_remainder_z
      - .offset:         168
        .size:           8
        .value_kind:     hidden_global_offset_x
      - .offset:         176
        .size:           8
        .value_kind:     hidden_global_offset_y
      - .offset:         184
        .size:           8
        .value_kind:     hidden_global_offset_z
      - .offset:         192
        .size:           2
        .value_kind:     hidden_grid_dims
      - .offset:         216
        .size:           8
        .value_kind:     hidden_multigrid_sync_arg
      - .offset:         248
        .size:           4
        .value_kind:     hidden_dynamic_lds_size
    .group_segment_fixed_size: 0
    .kernarg_segment_align: 8
    .kernarg_segment_size: 384
    .language:       OpenCL C
    .language_version:
      - 2
      - 0
    .max_flat_workgroup_size: 512
    .name:           _Z9trunk_fwd4Args
    .private_segment_fixed_size: 0
    .sgpr_count:     101
    .sgpr_spill_count: 0
    .symbol:         _Z9trunk_fwd4Args.kd
    .uniform_work_group_size: 1
    .uses_dynamic_stack: false
    .vgpr_count:     252
    .vgpr_spill_count: 0
    .wavefront_size: 64
